# attention unit epilogue: the workgroup barrier moved from the epilogue start to its end (in front of the next LDS writes), so early waves run their epilogue while late waves finish the last tile
# speedup vs baseline: 1.0085x; 1.0085x over previous
; __device__ __forceinline__ void dattn_unit(LAS unsigned char* lds, int b, int h, int qb, const bf16* Q, const bf16* K, const bf16* V, bf16* YB, float lam, const float* subg, float oml, int tid) {
;     ...
;     const float l1 = lsum[0] + __shfl_xor(lsum[0], 32), l2 = lsum[1] + __shfl_xor(lsum[1], 32);
;     const float i1 = 1.0f / l1, i2 = lam / l2; float ss = 0.f;
; #pragma unroll
;     for (int cb = 0; cb < 4; ++cb)
; #pragma unroll
;         for (int r = 0; r < 16; ++r) { const float y = o[0][cb][r] * i1 - o[1][cb][r] * i2; o[0][cb][r] = y; ss += y * y; }
; __device__ __forceinline__ void attn_super(LAS unsigned char* lds, int su, const bf16* Q, const bf16* K, const bf16* VA, bf16* YB, const float* tabg, float lam, const float* subg, float oml, int tid) {
;     ...
;     for (int qi = 0; qi < 4; ++qi) {
;         const int qb = (qi == 0) ? s : (qi == 1) ? 7 - s : (qi == 2) ? 8 + s : 15 - s;
;         dattn_unit(lds, b, h, qb, Q, K, VA, YB, lam, subg, oml, tid);
.LBB0_219:
	v_cmp_lt_i32_e32 vcc, v252, v246
	s_nop 3
	v_mov_b32_e32 v135, v98
	v_mov_b32_e32 v98, v97
	v_cndmask_b32_e32 v128, v245, v252, vcc
	v_lshlrev_b32_e32 v139, 2, v128
	ds_bpermute_b32 v128, v139, v179
	ds_bpermute_b32 v129, v139, v181
	s_waitcnt lgkmcnt(0)
	v_add_f32_e32 v128, v179, v128
	v_div_scale_f32 v130, s[46:47], v128, v128, 1.0
	v_rcp_f32_e32 v131, v130
	v_add_f32_e32 v129, v181, v129
	v_lshlrev_b32_e32 v208, 1, v160
	s_add_i32 s55, s55, 1
	v_fma_f32 v132, -v130, v131, 1.0
	v_fmac_f32_e32 v131, v132, v131
	v_div_scale_f32 v132, vcc, 1.0, v128, 1.0
	v_mul_f32_e32 v133, v132, v131
	v_fma_f32 v134, -v130, v133, v132
	v_fmac_f32_e32 v133, v134, v131
	v_fma_f32 v130, -v130, v133, v132
	v_div_fmas_f32 v130, v130, v131, v133
	v_div_fixup_f32 v136, v130, v128, 1.0
	v_div_scale_f32 v128, s[46:47], v129, v129, v186
	v_rcp_f32_e32 v130, v128
	v_mov_b32_e32 v134, v96
	s_cmp_lg_u32 s55, 4
	v_fma_f32 v131, -v128, v130, 1.0
	v_fmac_f32_e32 v130, v131, v130
	v_div_scale_f32 v131, vcc, v186, v129, v186
	v_mul_f32_e32 v132, v131, v130
	v_fma_f32 v133, -v128, v132, v131
	v_fmac_f32_e32 v132, v133, v130
	v_fma_f32 v128, -v128, v132, v131
	v_div_fmas_f32 v128, v128, v130, v132
	v_div_fixup_f32 v138, v128, v129, v186
	v_pk_mul_f32 v[12:13], v[12:13], v[138:139] op_sel_hi:[1,0]
	v_mov_b32_e32 v129, v114
	v_pk_fma_f32 v[28:29], v[28:29], v[136:137], v[12:13] op_sel_hi:[1,0,1] neg_lo:[0,0,1] neg_hi:[0,0,1]
	v_pk_mul_f32 v[12:13], v[14:15], v[138:139] op_sel_hi:[1,0]
	v_mov_b32_e32 v114, v113
	v_pk_fma_f32 v[30:31], v[30:31], v[136:137], v[12:13] op_sel_hi:[1,0,1] neg_lo:[0,0,1] neg_hi:[0,0,1]
	v_lshlrev_b32_e32 v137, 2, v160
	v_pk_mul_f32 v[96:97], v[98:99], v[138:139] op_sel_hi:[1,0]
	v_mov_b32_e32 v98, v100
	v_mov_b32_e32 v99, v102
	v_mov_b32_e32 v128, v112
	v_pk_mul_f32 v[134:135], v[134:135], v[138:139] op_sel_hi:[1,0]
	v_pk_fma_f32 v[112:113], v[114:115], v[136:137], v[96:97] op_sel_hi:[1,0,1] neg_lo:[0,0,1] neg_hi:[0,0,1]
	v_mov_b32_e32 v96, v116
	v_mov_b32_e32 v97, v118
	v_pk_mul_f32 v[98:99], v[98:99], v[138:139] op_sel_hi:[1,0]
	v_mov_b32_e32 v102, v101
	v_pk_fma_f32 v[128:129], v[128:129], v[136:137], v[134:135] op_sel_hi:[1,0,1] neg_lo:[0,0,1] neg_hi:[0,0,1]
	v_pk_fma_f32 v[134:135], v[96:97], v[136:137], v[98:99] op_sel_hi:[1,0,1] neg_lo:[0,0,1] neg_hi:[0,0,1]
	v_mov_b32_e32 v118, v117
	v_pk_mul_f32 v[96:97], v[102:103], v[138:139] op_sel_hi:[1,0]
	v_mov_b32_e32 v98, v104
	v_mov_b32_e32 v99, v106
	v_pk_fma_f32 v[118:119], v[118:119], v[136:137], v[96:97] op_sel_hi:[1,0,1] neg_lo:[0,0,1] neg_hi:[0,0,1]
	v_mov_b32_e32 v96, v120
	v_mov_b32_e32 v97, v122
	v_pk_mul_f32 v[98:99], v[98:99], v[138:139] op_sel_hi:[1,0]
	v_mov_b32_e32 v106, v105
	v_pk_fma_f32 v[116:117], v[96:97], v[136:137], v[98:99] op_sel_hi:[1,0,1] neg_lo:[0,0,1] neg_hi:[0,0,1]
	v_mov_b32_e32 v122, v121
	v_pk_mul_f32 v[96:97], v[106:107], v[138:139] op_sel_hi:[1,0]
	v_mov_b32_e32 v98, v108
	v_mov_b32_e32 v99, v110
	v_pk_fma_f32 v[106:107], v[122:123], v[136:137], v[96:97] op_sel_hi:[1,0,1] neg_lo:[0,0,1] neg_hi:[0,0,1]
	v_mov_b32_e32 v96, v124
	v_mov_b32_e32 v97, v126
	v_pk_mul_f32 v[98:99], v[98:99], v[138:139] op_sel_hi:[1,0]
	v_mov_b32_e32 v110, v109
	v_pk_fma_f32 v[102:103], v[96:97], v[136:137], v[98:99] op_sel_hi:[1,0,1] neg_lo:[0,0,1] neg_hi:[0,0,1]
	v_mov_b32_e32 v126, v125
	v_pk_mul_f32 v[96:97], v[110:111], v[138:139] op_sel_hi:[1,0]
	v_mov_b32_e32 v98, v64
	v_mov_b32_e32 v99, v66
	v_mov_b32_e32 v66, v65
	v_pk_fma_f32 v[104:105], v[126:127], v[136:137], v[96:97] op_sel_hi:[1,0,1] neg_lo:[0,0,1] neg_hi:[0,0,1]
	v_mov_b32_e32 v96, v80
	v_mov_b32_e32 v97, v82
	v_pk_mul_f32 v[98:99], v[98:99], v[138:139] op_sel_hi:[1,0]
	v_mov_b32_e32 v82, v81
	v_pk_mul_f32 v[64:65], v[66:67], v[138:139] op_sel_hi:[1,0]
	v_mov_b32_e32 v66, v68
	v_mov_b32_e32 v67, v70
	v_pk_fma_f32 v[100:101], v[96:97], v[136:137], v[98:99] op_sel_hi:[1,0,1] neg_lo:[0,0,1] neg_hi:[0,0,1]
	v_pk_fma_f32 v[98:99], v[82:83], v[136:137], v[64:65] op_sel_hi:[1,0,1] neg_lo:[0,0,1] neg_hi:[0,0,1]
	v_mov_b32_e32 v64, v84
	v_mov_b32_e32 v65, v86
	v_pk_mul_f32 v[66:67], v[66:67], v[138:139] op_sel_hi:[1,0]
	v_mov_b32_e32 v70, v69
	v_pk_fma_f32 v[96:97], v[64:65], v[136:137], v[66:67] op_sel_hi:[1,0,1] neg_lo:[0,0,1] neg_hi:[0,0,1]
	v_mov_b32_e32 v86, v85
	v_pk_mul_f32 v[64:65], v[70:71], v[138:139] op_sel_hi:[1,0]
	v_mov_b32_e32 v66, v72
	v_mov_b32_e32 v67, v74
	v_pk_fma_f32 v[82:83], v[86:87], v[136:137], v[64:65] op_sel_hi:[1,0,1] neg_lo:[0,0,1] neg_hi:[0,0,1]
	v_mov_b32_e32 v64, v88
	v_mov_b32_e32 v65, v90
	v_pk_mul_f32 v[66:67], v[66:67], v[138:139] op_sel_hi:[1,0]
	v_mov_b32_e32 v74, v73
	v_pk_fma_f32 v[80:81], v[64:65], v[136:137], v[66:67] op_sel_hi:[1,0,1] neg_lo:[0,0,1] neg_hi:[0,0,1]
	v_mov_b32_e32 v90, v89
	v_pk_mul_f32 v[64:65], v[74:75], v[138:139] op_sel_hi:[1,0]
	v_mov_b32_e32 v66, v76
	v_mov_b32_e32 v67, v78
	v_pk_fma_f32 v[74:75], v[90:91], v[136:137], v[64:65] op_sel_hi:[1,0,1] neg_lo:[0,0,1] neg_hi:[0,0,1]
	v_mov_b32_e32 v64, v92
	v_mov_b32_e32 v65, v94
	v_pk_mul_f32 v[66:67], v[66:67], v[138:139] op_sel_hi:[1,0]
	v_mov_b32_e32 v78, v77
	v_pk_fma_f32 v[72:73], v[64:65], v[136:137], v[66:67] op_sel_hi:[1,0,1] neg_lo:[0,0,1] neg_hi:[0,0,1]
	v_mov_b32_e32 v94, v93
	v_pk_mul_f32 v[64:65], v[78:79], v[138:139] op_sel_hi:[1,0]
	v_mov_b32_e32 v66, v32
	v_mov_b32_e32 v67, v34
	v_mov_b32_e32 v34, v33
	v_pk_fma_f32 v[70:71], v[94:95], v[136:137], v[64:65] op_sel_hi:[1,0,1] neg_lo:[0,0,1] neg_hi:[0,0,1]
	v_mov_b32_e32 v64, v48
	v_mov_b32_e32 v65, v50
	v_pk_mul_f32 v[66:67], v[66:67], v[138:139] op_sel_hi:[1,0]
	v_mov_b32_e32 v50, v49
	v_pk_mul_f32 v[32:33], v[34:35], v[138:139] op_sel_hi:[1,0]
; __device__ __forceinline__ void dattn_unit(LAS unsigned char* lds, int b, int h, int qb, const bf16* Q, const bf16* K, const bf16* V, bf16* YB, float lam, const float* subg, float oml, int tid) {
;     ...
;         for (int r = 0; r < 16; ++r) { const float y = o[0][cb][r] * i1 - o[1][cb][r] * i2; o[0][cb][r] = y; ss += y * y; }
;     ss += __shfl_xor(ss, 32);
;     const float rstd = rsqrtf(ss * (1.f / 128.f) + EPS) * oml;
;     bf16* op = YB + (rowb + q) * 1024 + h * 128;
; #pragma unroll
;     for (int cb = 0; cb < 4; ++cb)
; #pragma unroll
;         for (int rg = 0; rg < 4; ++rg) { const int c = 32 * cb + 8 * rg + 4 * hi; const f32x4 g = *(const f32x4*)(subg + c);
	v_mov_b32_e32 v34, v36
	v_mov_b32_e32 v35, v38
	v_pk_fma_f32 v[68:69], v[64:65], v[136:137], v[66:67] op_sel_hi:[1,0,1] neg_lo:[0,0,1] neg_hi:[0,0,1]
	v_pk_fma_f32 v[66:67], v[50:51], v[136:137], v[32:33] op_sel_hi:[1,0,1] neg_lo:[0,0,1] neg_hi:[0,0,1]
	v_mov_b32_e32 v32, v52
	v_mov_b32_e32 v33, v54
	v_pk_mul_f32 v[34:35], v[34:35], v[138:139] op_sel_hi:[1,0]
	v_mov_b32_e32 v38, v37
	v_pk_fma_f32 v[64:65], v[32:33], v[136:137], v[34:35] op_sel_hi:[1,0,1] neg_lo:[0,0,1] neg_hi:[0,0,1]
	v_mov_b32_e32 v54, v53
	v_pk_mul_f32 v[32:33], v[38:39], v[138:139] op_sel_hi:[1,0]
	v_mov_b32_e32 v34, v40
	v_mov_b32_e32 v35, v42
	v_pk_fma_f32 v[50:51], v[54:55], v[136:137], v[32:33] op_sel_hi:[1,0,1] neg_lo:[0,0,1] neg_hi:[0,0,1]
	v_mov_b32_e32 v32, v56
	v_mov_b32_e32 v33, v58
	v_pk_mul_f32 v[34:35], v[34:35], v[138:139] op_sel_hi:[1,0]
	v_mov_b32_e32 v42, v41
	v_pk_fma_f32 v[48:49], v[32:33], v[136:137], v[34:35] op_sel_hi:[1,0,1] neg_lo:[0,0,1] neg_hi:[0,0,1]
	v_mov_b32_e32 v58, v57
	v_pk_mul_f32 v[32:33], v[42:43], v[138:139] op_sel_hi:[1,0]
	v_mov_b32_e32 v34, v44
	v_mov_b32_e32 v35, v46
	v_pk_fma_f32 v[38:39], v[58:59], v[136:137], v[32:33] op_sel_hi:[1,0,1] neg_lo:[0,0,1] neg_hi:[0,0,1]
	v_mov_b32_e32 v32, v60
	v_mov_b32_e32 v33, v62
	v_pk_mul_f32 v[34:35], v[34:35], v[138:139] op_sel_hi:[1,0]
	v_mov_b32_e32 v46, v45
	v_pk_fma_f32 v[36:37], v[32:33], v[136:137], v[34:35] op_sel_hi:[1,0,1] neg_lo:[0,0,1] neg_hi:[0,0,1]
	v_mov_b32_e32 v62, v61
	v_pk_mul_f32 v[32:33], v[46:47], v[138:139] op_sel_hi:[1,0]
	v_mov_b32_e32 v47, v2
	v_mov_b32_e32 v2, v1
	global_load_dwordx4 v[12:15], v137, s[4:5]
	global_load_dwordx4 v[212:215], v137, s[4:5] offset:32
	global_load_dwordx4 v[216:219], v137, s[4:5] offset:64
	global_load_dwordx4 v[220:223], v137, s[4:5] offset:96
	global_load_dwordx4 v[224:227], v137, s[4:5] offset:128
	global_load_dwordx4 v[228:231], v137, s[4:5] offset:160
	global_load_dwordx4 v[232:235], v137, s[4:5] offset:192
	global_load_dwordx4 v[236:239], v137, s[4:5] offset:224
	global_load_dwordx4 v[240:243], v137, s[4:5] offset:256
	global_load_dwordx4 v[192:195], v137, s[4:5] offset:288
	global_load_dwordx4 v[196:199], v137, s[4:5] offset:320
	global_load_dwordx4 v[200:203], v137, s[4:5] offset:352
	global_load_dwordx4 v[204:207], v137, s[4:5] offset:384
	global_load_dwordx4 v[164:167], v137, s[4:5] offset:416
	global_load_dwordx4 v[168:171], v137, s[4:5] offset:448
	global_load_dwordx4 v[172:175], v137, s[4:5] offset:480
	v_pk_mul_f32 v[140:141], v[128:129], v[128:129]
	v_pk_mul_f32 v[142:143], v[112:113], v[112:113]
	v_pk_fma_f32 v[34:35], v[62:63], v[136:137], v[32:33] op_sel_hi:[1,0,1] neg_lo:[0,0,1] neg_hi:[0,0,1]
	v_mov_b32_e32 v33, v18
	v_mov_b32_e32 v46, v0
	v_mov_b32_e32 v18, v17
	v_pk_mul_f32 v[0:1], v[2:3], v[138:139] op_sel_hi:[1,0]
	v_pk_mul_f32 v[144:145], v[134:135], v[134:135]
	v_pk_fma_f32 v[18:19], v[18:19], v[136:137], v[0:1] op_sel_hi:[1,0,1] neg_lo:[0,0,1] neg_hi:[0,0,1]
	v_mov_b32_e32 v0, v20
	v_add_f32_e32 v20, v140, v142
	v_add_f32_e32 v20, v141, v20
	v_add_f32_e32 v20, v143, v20
	v_pk_mul_f32 v[146:147], v[118:119], v[118:119]
	v_add_f32_e32 v20, v144, v20
	v_add_f32_e32 v20, v146, v20
	v_add_f32_e32 v20, v145, v20
	v_pk_mul_f32 v[148:149], v[116:117], v[116:117]
	v_add_f32_e32 v20, v147, v20
	v_pk_mul_f32 v[120:121], v[106:107], v[106:107]
	v_add_f32_e32 v20, v148, v20
	v_add_f32_e32 v20, v120, v20
	v_add_f32_e32 v20, v149, v20
	v_pk_mul_f32 v[122:123], v[102:103], v[102:103]
	v_add_f32_e32 v20, v121, v20
	v_pk_mul_f32 v[108:109], v[104:105], v[104:105]
	v_add_f32_e32 v20, v122, v20
	v_add_f32_e32 v20, v108, v20
	v_add_f32_e32 v20, v123, v20
	v_pk_mul_f32 v[110:111], v[100:101], v[100:101]
	v_add_f32_e32 v20, v109, v20
	v_pk_mul_f32 v[124:125], v[98:99], v[98:99]
	v_add_f32_e32 v20, v110, v20
	v_add_f32_e32 v20, v124, v20
	v_add_f32_e32 v20, v111, v20
	v_pk_mul_f32 v[126:127], v[96:97], v[96:97]
	v_add_f32_e32 v20, v125, v20
	v_pk_mul_f32 v[84:85], v[82:83], v[82:83]
	v_add_f32_e32 v20, v126, v20
	v_add_f32_e32 v20, v84, v20
	v_add_f32_e32 v20, v127, v20
	v_pk_mul_f32 v[86:87], v[80:81], v[80:81]
	v_add_f32_e32 v20, v85, v20
	v_pk_mul_f32 v[88:89], v[74:75], v[74:75]
	v_add_f32_e32 v20, v86, v20
	v_add_f32_e32 v20, v88, v20
	v_add_f32_e32 v20, v87, v20
	v_pk_mul_f32 v[90:91], v[72:73], v[72:73]
	v_add_f32_e32 v20, v89, v20
	v_pk_mul_f32 v[76:77], v[70:71], v[70:71]
	v_add_f32_e32 v20, v90, v20
	v_add_f32_e32 v20, v76, v20
	v_add_f32_e32 v20, v91, v20
	v_pk_mul_f32 v[78:79], v[68:69], v[68:69]
	v_add_f32_e32 v20, v77, v20
	v_pk_mul_f32 v[92:93], v[66:67], v[66:67]
	v_add_f32_e32 v20, v78, v20
	v_add_f32_e32 v20, v92, v20
	v_add_f32_e32 v20, v79, v20
	v_pk_mul_f32 v[94:95], v[64:65], v[64:65]
	v_add_f32_e32 v20, v93, v20
	v_pk_mul_f32 v[52:53], v[50:51], v[50:51]
	v_add_f32_e32 v20, v94, v20
	v_add_f32_e32 v20, v52, v20
	v_add_f32_e32 v20, v95, v20
	v_pk_mul_f32 v[54:55], v[48:49], v[48:49]
	v_add_f32_e32 v20, v53, v20
	v_pk_mul_f32 v[40:41], v[38:39], v[38:39]
	v_add_f32_e32 v20, v54, v20
	v_add_f32_e32 v20, v40, v20
	v_add_f32_e32 v20, v55, v20
	v_pk_mul_f32 v[42:43], v[36:37], v[36:37]
	v_add_f32_e32 v20, v41, v20
	v_pk_mul_f32 v[44:45], v[34:35], v[34:35]
	v_add_f32_e32 v20, v42, v20
	v_mov_b32_e32 v32, v16
	v_pk_mul_f32 v[46:47], v[46:47], v[138:139] op_sel_hi:[1,0]
	v_add_f32_e32 v20, v44, v20
	v_pk_fma_f32 v[32:33], v[32:33], v[136:137], v[46:47] op_sel_hi:[1,0,1] neg_lo:[0,0,1] neg_hi:[0,0,1]
	v_mov_b32_e32 v2, v4
	v_mov_b32_e32 v3, v6
	v_add_f32_e32 v20, v43, v20
	v_pk_mul_f32 v[46:47], v[32:33], v[32:33]
	v_mov_b32_e32 v1, v22
	v_pk_mul_f32 v[2:3], v[2:3], v[138:139] op_sel_hi:[1,0]
	v_mov_b32_e32 v6, v5
; __device__ __forceinline__ unsigned pk2(float lo, float hi) { return f2bf(lo) | (f2bf(hi) << 16); }
; __device__ __forceinline__ void dattn_unit(LAS unsigned char* lds, int b, int h, int qb, const bf16* Q, const bf16* K, const bf16* V, bf16* YB, float lam, const float* subg, float oml, int tid) {
;     ...
;     ss += __shfl_xor(ss, 32);
;     const float rstd = rsqrtf(ss * (1.f / 128.f) + EPS) * oml;
;     bf16* op = YB + (rowb + q) * 1024 + h * 128;
; #pragma unroll
;     for (int cb = 0; cb < 4; ++cb)
; #pragma unroll
;         for (int rg = 0; rg < 4; ++rg) { const int c = 32 * cb + 8 * rg + 4 * hi; const f32x4 g = *(const f32x4*)(subg + c);
;             v2u wv; wv.x = pk2(o[0][cb][4 * rg + 0] * rstd * g.x, o[0][cb][4 * rg + 1] * rstd * g.y); wv.y = pk2(o[0][cb][4 * rg + 2] * rstd * g.z, o[0][cb][4 * rg + 3] * rstd * g.w);
;             *(v2u*)(op + c) = wv; }
	v_add_f32_e32 v20, v45, v20
	v_pk_mul_f32 v[56:57], v[18:19], v[18:19]
	v_pk_fma_f32 v[16:17], v[0:1], v[136:137], v[2:3] op_sel_hi:[1,0,1] neg_lo:[0,0,1] neg_hi:[0,0,1]
	v_mov_b32_e32 v22, v21
	v_pk_mul_f32 v[0:1], v[6:7], v[138:139] op_sel_hi:[1,0]
	v_add_f32_e32 v20, v46, v20
	v_pk_fma_f32 v[4:5], v[22:23], v[136:137], v[0:1] op_sel_hi:[1,0,1] neg_lo:[0,0,1] neg_hi:[0,0,1]
	v_add_f32_e32 v20, v56, v20
	v_mov_b32_e32 v0, v5
	v_mov_b32_e32 v1, v17
	v_mov_b32_e32 v2, v8
	v_mov_b32_e32 v3, v10
	v_add_f32_e32 v20, v47, v20
	v_pk_mul_f32 v[6:7], v[0:1], v[0:1]
	v_mov_b32_e32 v0, v24
	v_mov_b32_e32 v1, v26
	v_pk_mul_f32 v[2:3], v[2:3], v[138:139] op_sel_hi:[1,0]
	v_mov_b32_e32 v10, v9
	v_add_f32_e32 v20, v57, v20
	v_pk_fma_f32 v[2:3], v[0:1], v[136:137], v[2:3] op_sel_hi:[1,0,1] neg_lo:[0,0,1] neg_hi:[0,0,1]
	v_mov_b32_e32 v26, v25
	v_pk_mul_f32 v[0:1], v[10:11], v[138:139] op_sel_hi:[1,0]
	v_fmac_f32_e32 v20, v16, v16
	v_pk_fma_f32 v[0:1], v[26:27], v[136:137], v[0:1] op_sel_hi:[1,0,1] neg_lo:[0,0,1] neg_hi:[0,0,1]
	v_fmac_f32_e32 v20, v4, v4
	v_mov_b32_e32 v8, v0
	v_mov_b32_e32 v9, v2
	v_add_f32_e32 v7, v7, v20
	v_pk_mul_f32 v[8:9], v[8:9], v[8:9]
	v_add_f32_e32 v6, v6, v7
	v_mov_b32_e32 v10, v1
	v_mov_b32_e32 v11, v3
	v_add_f32_e32 v6, v9, v6
	v_pk_mul_f32 v[10:11], v[10:11], v[10:11]
	v_add_f32_e32 v6, v8, v6
	v_add_f32_e32 v6, v11, v6
	v_pk_mul_f32 v[130:131], v[28:29], v[28:29]
	v_add_f32_e32 v6, v10, v6
	v_add_f32_e32 v6, v130, v6
	v_pk_mul_f32 v[132:133], v[30:31], v[30:31]
	v_add_f32_e32 v6, v131, v6
	v_add_f32_e32 v6, v132, v6
	v_add_f32_e32 v6, v133, v6
	ds_bpermute_b32 v7, v139, v6
	s_waitcnt vmcnt(15)
	v_mov_b32_e32 v114, v12
	v_mov_b32_e32 v115, v14
	v_mov_b32_e32 v14, v13
	v_lshl_add_u64 v[12:13], v[176:177], 0, v[208:209]
	s_waitcnt lgkmcnt(0)
	v_add_f32_e32 v6, v6, v7
	v_fmamk_f32 v6, v6, 0x3c000000, v210
	v_cmp_gt_f32_e32 vcc, s39, v6
	v_mul_f32_e32 v7, 0x4b800000, v6
	s_nop 0
	v_cndmask_b32_e32 v6, v6, v7, vcc
	v_rsq_f32_e32 v6, v6
	s_nop 0
	v_mul_f32_e32 v7, 0x45800000, v6
	v_cndmask_b32_e32 v6, v6, v7, vcc
	v_mul_f32_e32 v6, v187, v6
	v_pk_mul_f32 v[8:9], v[128:129], v[6:7] op_sel_hi:[1,0]
	v_pk_mul_f32 v[10:11], v[112:113], v[6:7] op_sel_hi:[1,0]
	v_pk_mul_f32 v[8:9], v[114:115], v[8:9]
	v_pk_mul_f32 v[10:11], v[14:15], v[10:11]
	v_cvt_pk_bf16_f32 v9, v9, v11
	v_cvt_pk_bf16_f32 v8, v8, v10
	global_store_dwordx2 v[12:13], v[8:9], off
	v_pk_mul_f32 v[14:15], v[134:135], v[6:7] op_sel_hi:[1,0]
	s_waitcnt vmcnt(15)
	v_mov_b32_e32 v8, v212
	v_mov_b32_e32 v9, v213
	v_mov_b32_e32 v10, v214
	v_mov_b32_e32 v11, v215
	v_mov_b32_e32 v20, v8
	v_mov_b32_e32 v21, v10
	v_pk_mul_f32 v[14:15], v[20:21], v[14:15]
	v_pk_mul_f32 v[20:21], v[118:119], v[6:7] op_sel_hi:[1,0]
	v_mov_b32_e32 v10, v9
	v_pk_mul_f32 v[8:9], v[10:11], v[20:21]
	v_cvt_pk_bf16_f32 v9, v15, v9
	v_cvt_pk_bf16_f32 v8, v14, v8
	global_store_dwordx2 v[12:13], v[8:9], off offset:16
	v_pk_mul_f32 v[14:15], v[116:117], v[6:7] op_sel_hi:[1,0]
	s_waitcnt vmcnt(15)
	v_mov_b32_e32 v8, v216
	v_mov_b32_e32 v9, v217
	v_mov_b32_e32 v10, v218
	v_mov_b32_e32 v11, v219
	v_mov_b32_e32 v20, v8
	v_mov_b32_e32 v21, v10
	v_pk_mul_f32 v[14:15], v[20:21], v[14:15]
	v_pk_mul_f32 v[20:21], v[106:107], v[6:7] op_sel_hi:[1,0]
	v_mov_b32_e32 v10, v9
	v_pk_mul_f32 v[8:9], v[10:11], v[20:21]
	v_cvt_pk_bf16_f32 v9, v15, v9
	v_cvt_pk_bf16_f32 v8, v14, v8
	global_store_dwordx2 v[12:13], v[8:9], off offset:32
	v_pk_mul_f32 v[14:15], v[102:103], v[6:7] op_sel_hi:[1,0]
	s_waitcnt vmcnt(15)
	v_mov_b32_e32 v8, v220
	v_mov_b32_e32 v9, v221
	v_mov_b32_e32 v10, v222
	v_mov_b32_e32 v11, v223
	v_mov_b32_e32 v20, v8
	v_mov_b32_e32 v21, v10
	v_pk_mul_f32 v[14:15], v[20:21], v[14:15]
	v_pk_mul_f32 v[20:21], v[104:105], v[6:7] op_sel_hi:[1,0]
	v_mov_b32_e32 v10, v9
	v_pk_mul_f32 v[8:9], v[10:11], v[20:21]
	v_cvt_pk_bf16_f32 v9, v15, v9
	v_cvt_pk_bf16_f32 v8, v14, v8
	global_store_dwordx2 v[12:13], v[8:9], off offset:48
	v_pk_mul_f32 v[14:15], v[100:101], v[6:7] op_sel_hi:[1,0]
	s_waitcnt vmcnt(15)
	v_mov_b32_e32 v8, v224
	v_mov_b32_e32 v9, v225
	v_mov_b32_e32 v10, v226
	v_mov_b32_e32 v11, v227
	v_mov_b32_e32 v20, v8
	v_mov_b32_e32 v21, v10
	v_pk_mul_f32 v[14:15], v[20:21], v[14:15]
	v_pk_mul_f32 v[20:21], v[98:99], v[6:7] op_sel_hi:[1,0]
	v_mov_b32_e32 v10, v9
	v_pk_mul_f32 v[8:9], v[10:11], v[20:21]
	v_cvt_pk_bf16_f32 v9, v15, v9
	v_cvt_pk_bf16_f32 v8, v14, v8
	global_store_dwordx2 v[12:13], v[8:9], off offset:64
	v_pk_mul_f32 v[14:15], v[96:97], v[6:7] op_sel_hi:[1,0]
	s_waitcnt vmcnt(15)
	v_mov_b32_e32 v8, v228
	v_mov_b32_e32 v9, v229
	v_mov_b32_e32 v10, v230
	v_mov_b32_e32 v11, v231
	v_mov_b32_e32 v20, v8
	v_mov_b32_e32 v21, v10
	v_pk_mul_f32 v[14:15], v[20:21], v[14:15]
	v_pk_mul_f32 v[20:21], v[82:83], v[6:7] op_sel_hi:[1,0]
	v_mov_b32_e32 v10, v9
	v_pk_mul_f32 v[8:9], v[10:11], v[20:21]
	v_cvt_pk_bf16_f32 v9, v15, v9
	v_cvt_pk_bf16_f32 v8, v14, v8
	global_store_dwordx2 v[12:13], v[8:9], off offset:80
	v_pk_mul_f32 v[14:15], v[80:81], v[6:7] op_sel_hi:[1,0]
	s_waitcnt vmcnt(15)
; __device__ __forceinline__ unsigned pk2(float lo, float hi) { return f2bf(lo) | (f2bf(hi) << 16); }
; __device__ __forceinline__ void dattn_unit(LAS unsigned char* lds, int b, int h, int qb, const bf16* Q, const bf16* K, const bf16* V, bf16* YB, float lam, const float* subg, float oml, int tid) {
;     ...
;     for (int cb = 0; cb < 4; ++cb)
; #pragma unroll
;         for (int rg = 0; rg < 4; ++rg) { const int c = 32 * cb + 8 * rg + 4 * hi; const f32x4 g = *(const f32x4*)(subg + c);
;             v2u wv; wv.x = pk2(o[0][cb][4 * rg + 0] * rstd * g.x, o[0][cb][4 * rg + 1] * rstd * g.y); wv.y = pk2(o[0][cb][4 * rg + 2] * rstd * g.z, o[0][cb][4 * rg + 3] * rstd * g.w);
;             *(v2u*)(op + c) = wv; }
; __device__ __forceinline__ void attn_super(LAS unsigned char* lds, int su, const bf16* Q, const bf16* K, const bf16* VA, bf16* YB, const float* tabg, float lam, const float* subg, float oml, int tid) {
;     ...
;     for (int qi = 0; qi < 4; ++qi) {
;         const int qb = (qi == 0) ? s : (qi == 1) ? 7 - s : (qi == 2) ? 8 + s : 15 - s;
;         dattn_unit(lds, b, h, qb, Q, K, VA, YB, lam, subg, oml, tid);
	v_mov_b32_e32 v8, v232
	v_mov_b32_e32 v9, v233
	v_mov_b32_e32 v10, v234
	v_mov_b32_e32 v11, v235
	v_mov_b32_e32 v20, v8
	v_mov_b32_e32 v21, v10
	v_pk_mul_f32 v[14:15], v[20:21], v[14:15]
	v_pk_mul_f32 v[20:21], v[74:75], v[6:7] op_sel_hi:[1,0]
	v_mov_b32_e32 v10, v9
	v_pk_mul_f32 v[8:9], v[10:11], v[20:21]
	v_cvt_pk_bf16_f32 v9, v15, v9
	v_cvt_pk_bf16_f32 v8, v14, v8
	global_store_dwordx2 v[12:13], v[8:9], off offset:96
	v_pk_mul_f32 v[14:15], v[72:73], v[6:7] op_sel_hi:[1,0]
	s_waitcnt vmcnt(15)
	v_mov_b32_e32 v8, v236
	v_mov_b32_e32 v9, v237
	v_mov_b32_e32 v10, v238
	v_mov_b32_e32 v11, v239
	v_mov_b32_e32 v20, v8
	v_mov_b32_e32 v21, v10
	v_pk_mul_f32 v[14:15], v[20:21], v[14:15]
	v_pk_mul_f32 v[20:21], v[70:71], v[6:7] op_sel_hi:[1,0]
	v_mov_b32_e32 v10, v9
	v_pk_mul_f32 v[8:9], v[10:11], v[20:21]
	v_cvt_pk_bf16_f32 v9, v15, v9
	v_cvt_pk_bf16_f32 v8, v14, v8
	global_store_dwordx2 v[12:13], v[8:9], off offset:112
	v_pk_mul_f32 v[14:15], v[68:69], v[6:7] op_sel_hi:[1,0]
	s_waitcnt vmcnt(15)
	v_mov_b32_e32 v8, v240
	v_mov_b32_e32 v9, v241
	v_mov_b32_e32 v10, v242
	v_mov_b32_e32 v11, v243
	v_mov_b32_e32 v20, v8
	v_mov_b32_e32 v21, v10
	v_pk_mul_f32 v[14:15], v[20:21], v[14:15]
	v_pk_mul_f32 v[20:21], v[66:67], v[6:7] op_sel_hi:[1,0]
	v_mov_b32_e32 v10, v9
	v_pk_mul_f32 v[8:9], v[10:11], v[20:21]
	v_cvt_pk_bf16_f32 v9, v15, v9
	v_cvt_pk_bf16_f32 v8, v14, v8
	global_store_dwordx2 v[12:13], v[8:9], off offset:128
	v_pk_mul_f32 v[14:15], v[64:65], v[6:7] op_sel_hi:[1,0]
	s_waitcnt vmcnt(15)
	v_mov_b32_e32 v8, v192
	v_mov_b32_e32 v9, v193
	v_mov_b32_e32 v10, v194
	v_mov_b32_e32 v11, v195
	v_mov_b32_e32 v20, v8
	v_mov_b32_e32 v21, v10
	v_pk_mul_f32 v[14:15], v[20:21], v[14:15]
	v_pk_mul_f32 v[20:21], v[50:51], v[6:7] op_sel_hi:[1,0]
	v_mov_b32_e32 v10, v9
	v_pk_mul_f32 v[8:9], v[10:11], v[20:21]
	v_cvt_pk_bf16_f32 v9, v15, v9
	v_cvt_pk_bf16_f32 v8, v14, v8
	global_store_dwordx2 v[12:13], v[8:9], off offset:144
	v_pk_mul_f32 v[14:15], v[48:49], v[6:7] op_sel_hi:[1,0]
	s_waitcnt vmcnt(15)
	v_mov_b32_e32 v8, v196
	v_mov_b32_e32 v9, v197
	v_mov_b32_e32 v10, v198
	v_mov_b32_e32 v11, v199
	v_mov_b32_e32 v20, v8
	v_mov_b32_e32 v21, v10
	v_pk_mul_f32 v[14:15], v[20:21], v[14:15]
	v_pk_mul_f32 v[20:21], v[38:39], v[6:7] op_sel_hi:[1,0]
	v_mov_b32_e32 v10, v9
	v_pk_mul_f32 v[8:9], v[10:11], v[20:21]
	v_cvt_pk_bf16_f32 v9, v15, v9
	v_cvt_pk_bf16_f32 v8, v14, v8
	global_store_dwordx2 v[12:13], v[8:9], off offset:160
	v_pk_mul_f32 v[14:15], v[36:37], v[6:7] op_sel_hi:[1,0]
	s_waitcnt vmcnt(15)
	v_mov_b32_e32 v8, v200
	v_mov_b32_e32 v9, v201
	v_mov_b32_e32 v10, v202
	v_mov_b32_e32 v11, v203
	v_mov_b32_e32 v20, v8
	v_mov_b32_e32 v21, v10
	v_pk_mul_f32 v[14:15], v[20:21], v[14:15]
	v_pk_mul_f32 v[20:21], v[34:35], v[6:7] op_sel_hi:[1,0]
	v_mov_b32_e32 v10, v9
	v_pk_mul_f32 v[8:9], v[10:11], v[20:21]
	v_cvt_pk_bf16_f32 v9, v15, v9
	v_cvt_pk_bf16_f32 v8, v14, v8
	global_store_dwordx2 v[12:13], v[8:9], off offset:176
	v_pk_mul_f32 v[14:15], v[32:33], v[6:7] op_sel_hi:[1,0]
	v_pk_mul_f32 v[18:19], v[18:19], v[6:7] op_sel_hi:[1,0]
	s_waitcnt vmcnt(15)
	v_mov_b32_e32 v8, v204
	v_mov_b32_e32 v9, v205
	v_mov_b32_e32 v10, v206
	v_mov_b32_e32 v11, v207
	v_mov_b32_e32 v20, v8
	v_mov_b32_e32 v21, v10
	v_pk_mul_f32 v[14:15], v[20:21], v[14:15]
	v_mov_b32_e32 v10, v9
	v_pk_mul_f32 v[8:9], v[10:11], v[18:19]
	v_cvt_pk_bf16_f32 v9, v15, v9
	v_cvt_pk_bf16_f32 v8, v14, v8
	global_store_dwordx2 v[12:13], v[8:9], off offset:192
	v_pk_mul_f32 v[14:15], v[16:17], v[6:7] op_sel_hi:[1,0]
	v_pk_mul_f32 v[4:5], v[4:5], v[6:7] op_sel_hi:[1,0]
	s_waitcnt vmcnt(15)
	v_mov_b32_e32 v8, v164
	v_mov_b32_e32 v9, v165
	v_mov_b32_e32 v10, v166
	v_mov_b32_e32 v11, v167
	v_mov_b32_e32 v17, v10
	v_mov_b32_e32 v10, v9
	v_mov_b32_e32 v16, v8
	v_pk_mul_f32 v[4:5], v[10:11], v[4:5]
	v_pk_mul_f32 v[14:15], v[16:17], v[14:15]
	v_cvt_pk_bf16_f32 v5, v15, v5
	v_cvt_pk_bf16_f32 v4, v14, v4
	global_store_dwordx2 v[12:13], v[4:5], off offset:208
	v_pk_mul_f32 v[2:3], v[2:3], v[6:7] op_sel_hi:[1,0]
	v_pk_mul_f32 v[0:1], v[0:1], v[6:7] op_sel_hi:[1,0]
	s_waitcnt vmcnt(15)
	v_mov_b32_e32 v8, v168
	v_mov_b32_e32 v9, v169
	v_mov_b32_e32 v10, v170
	v_mov_b32_e32 v11, v171
	v_mov_b32_e32 v4, v8
	v_mov_b32_e32 v5, v10
	v_pk_mul_f32 v[2:3], v[4:5], v[2:3]
	v_mov_b32_e32 v10, v9
	v_pk_mul_f32 v[0:1], v[10:11], v[0:1]
	v_cvt_pk_bf16_f32 v1, v3, v1
	v_cvt_pk_bf16_f32 v0, v2, v0
	global_store_dwordx2 v[12:13], v[0:1], off offset:224
	v_mov_b32_e32 v4, v28
	v_mov_b32_e32 v5, v30
	v_pk_mul_f32 v[4:5], v[4:5], v[6:7] op_sel_hi:[1,0]
	v_mov_b32_e32 v30, v29
	v_pk_mul_f32 v[6:7], v[30:31], v[6:7] op_sel_hi:[1,0]
	s_waitcnt vmcnt(15)
	v_mov_b32_e32 v0, v172
	v_mov_b32_e32 v1, v173
	v_mov_b32_e32 v2, v174
	v_mov_b32_e32 v3, v175
	v_mov_b32_e32 v8, v0
	v_mov_b32_e32 v9, v2
	v_pk_mul_f32 v[4:5], v[8:9], v[4:5]
	v_mov_b32_e32 v2, v1
	v_pk_mul_f32 v[0:1], v[2:3], v[6:7]
	v_cvt_pk_bf16_f32 v1, v5, v1
	v_cvt_pk_bf16_f32 v0, v4, v0
	global_store_dwordx2 v[12:13], v[0:1], off offset:240
	s_barrier
	s_cbranch_scc0 .LBB0_213
